# post phase: 32-lane sum reductions of q/k head norms via DPP (quad_perm, row_half_mirror, row_mirror) + v_permlane16_swap instead of 5 ds_bpermute round trips
# speedup vs baseline: 1.0048x; 1.0048x over previous
.LBB0_319:
	s_or_b64 exec, exec, s[0:1]
	global_load_dwordx2 v[64:65], v[8:9], off
	global_load_dwordx2 v[60:61], v[10:11], off
	global_load_dwordx2 v[58:59], v[12:13], off
	global_load_dwordx2 v[70:71], v[6:7], off
	v_and_b32_e32 v39, 64, v213
	v_add_u32_e32 v45, 64, v39
	s_waitcnt vmcnt(13)
	v_lshlrev_b32_e32 v66, 16, v37
	v_and_b32_e32 v67, 0xffff0000, v37
	v_xor_b32_e32 v37, 16, v213
	v_cmp_lt_i32_e32 vcc, v37, v45
	v_xor_b32_e32 v41, 4, v213
	v_xor_b32_e32 v43, 2, v213
	v_cndmask_b32_e32 v37, v213, v37, vcc
	v_lshlrev_b32_e32 v39, 2, v37
	v_xor_b32_e32 v37, 8, v213
	v_cmp_lt_i32_e32 vcc, v37, v45
	v_xor_b32_e32 v68, 1, v213
	s_mov_b32 s0, 0x800000
	v_cndmask_b32_e32 v37, v213, v37, vcc
	v_cmp_lt_i32_e32 vcc, v41, v45
	v_lshlrev_b32_e32 v37, 2, v37
	s_nop 0
	v_cndmask_b32_e32 v41, v213, v41, vcc
	v_cmp_lt_i32_e32 vcc, v43, v45
	v_lshlrev_b32_e32 v41, 2, v41
	s_nop 0
	v_cndmask_b32_e32 v43, v213, v43, vcc
	v_cmp_lt_i32_e32 vcc, v68, v45
	v_lshlrev_b32_e32 v43, 2, v43
	s_nop 0
	v_cndmask_b32_e32 v45, v213, v68, vcc
	v_pk_mul_f32 v[68:69], v[66:67], v[66:67]
	v_lshlrev_b32_e32 v45, 2, v45
	v_add_f32_e32 v68, v68, v69
	s_waitcnt lgkmcnt(0)
	s_nop 1
	v_add_f32_dpp v68, v68, v68 quad_perm:[1,0,3,2] row_mask:0xf bank_mask:0xf
	s_nop 1
	v_add_f32_dpp v68, v68, v68 quad_perm:[2,3,0,1] row_mask:0xf bank_mask:0xf
	s_nop 1
	v_add_f32_dpp v68, v68, v68 row_half_mirror row_mask:0xf bank_mask:0xf
	s_nop 1
	v_add_f32_dpp v68, v68, v68 row_mirror row_mask:0xf bank_mask:0xf
	v_mov_b32_e32 v69, v68
	s_nop 1
	v_permlane16_swap_b32_e32 v69, v68
	v_add_f32_e32 v68, v68, v69
	v_fmamk_f32 v68, v68, 0x3c800000, v212
	v_cmp_gt_f32_e32 vcc, s0, v68
	v_mul_f32_e32 v69, 0x4b800000, v68
	s_nop 0
	v_cndmask_b32_e32 v68, v68, v69, vcc
	v_rsq_f32_e32 v68, v68
	s_nop 0
	v_mul_f32_e32 v69, 0x45800000, v68
	v_cndmask_b32_e32 v68, v68, v69, vcc
	v_pk_mul_f32 v[66:67], v[68:69], v[66:67] op_sel_hi:[0,1]
	s_waitcnt vmcnt(0)
	v_pk_mul_f32 v[72:73], v[70:71], v[66:67]
	s_and_saveexec_b64 s[0:1], s[40:41]
	s_cbranch_execz .LBB0_321
	ds_bpermute_b32 v66, v37, v72
	ds_bpermute_b32 v67, v37, v73
	s_waitcnt lgkmcnt(0)
	v_pk_mul_f32 v[66:67], v[54:55], v[66:67]
	s_nop 0
	v_pk_fma_f32 v[72:73], v[52:53], v[72:73], v[66:67]
.LBB0_321:
	s_or_b64 exec, exec, s[0:1]
	v_lshlrev_b64 v[66:67], 10, v[62:63]
	s_mov_b32 s0, 0x3e38aa3b
	v_lshl_add_u64 v[68:69], s[2:3], 0, v[66:67]
	v_pk_mul_f32 v[72:73], v[72:73], s[0:1] op_sel_hi:[1,0]
	s_mov_b32 s0, 0x800000
	v_cvt_pk_bf16_f32 v75, v72, v73
	v_lshl_add_u64 v[72:73], v[68:69], 0, v[116:117]
	v_add_co_u32_e32 v82, vcc, 0x126ce000, v72
	s_nop 1
	v_addc_co_u32_e32 v83, vcc, 0, v73, vcc
	global_store_dword v[82:83], v75, off
	v_lshlrev_b32_e32 v82, 16, v74
	v_and_b32_e32 v83, 0xffff0000, v74
	v_pk_mul_f32 v[74:75], v[82:83], v[82:83]
	s_nop 0
	v_add_f32_e32 v74, v74, v75
	s_waitcnt lgkmcnt(0)
	s_nop 1
	v_add_f32_dpp v74, v74, v74 quad_perm:[1,0,3,2] row_mask:0xf bank_mask:0xf
	s_nop 1
	v_add_f32_dpp v74, v74, v74 quad_perm:[2,3,0,1] row_mask:0xf bank_mask:0xf
	s_nop 1
	v_add_f32_dpp v74, v74, v74 row_half_mirror row_mask:0xf bank_mask:0xf
	s_nop 1
	v_add_f32_dpp v74, v74, v74 row_mirror row_mask:0xf bank_mask:0xf
	v_mov_b32_e32 v75, v74
	s_nop 1
	v_permlane16_swap_b32_e32 v75, v74
	v_add_f32_e32 v74, v74, v75
	v_fmamk_f32 v74, v74, 0x3c800000, v212
	v_cmp_gt_f32_e32 vcc, s0, v74
	v_mul_f32_e32 v75, 0x4b800000, v74
	s_nop 0
	v_cndmask_b32_e32 v74, v74, v75, vcc
	v_rsq_f32_e32 v74, v74
	s_nop 0
	v_mul_f32_e32 v75, 0x45800000, v74
	v_cndmask_b32_e32 v74, v74, v75, vcc
	v_pk_mul_f32 v[74:75], v[74:75], v[82:83] op_sel_hi:[0,1]
	v_pk_mul_f32 v[74:75], v[70:71], v[74:75]
	s_and_saveexec_b64 s[0:1], s[40:41]
	s_cbranch_execz .LBB0_323
	ds_bpermute_b32 v82, v37, v74
	ds_bpermute_b32 v83, v37, v75
	s_waitcnt lgkmcnt(0)
	v_pk_mul_f32 v[82:83], v[54:55], v[82:83]
	s_nop 0
	v_pk_fma_f32 v[74:75], v[52:53], v[74:75], v[82:83]
.LBB0_323:
	s_or_b64 exec, exec, s[0:1]
	s_mov_b32 s0, 0x3e38aa3b
	v_pk_mul_f32 v[74:75], v[74:75], s[0:1] op_sel_hi:[1,0]
	v_add_co_u32_e32 v72, vcc, 0x126ce000, v72
	v_cvt_pk_bf16_f32 v74, v74, v75
	s_nop 0
	v_addc_co_u32_e32 v73, vcc, 0, v73, vcc
	global_store_dword v[72:73], v74, off offset:256
	v_lshlrev_b32_e32 v72, 16, v81
	v_and_b32_e32 v73, 0xffff0000, v81
	v_pk_mul_f32 v[74:75], v[72:73], v[72:73]
	s_mov_b32 s0, 0x800000
	v_add_f32_e32 v74, v74, v75
	s_waitcnt lgkmcnt(0)
	s_nop 1
	v_add_f32_dpp v74, v74, v74 quad_perm:[1,0,3,2] row_mask:0xf bank_mask:0xf
	s_nop 1
	v_add_f32_dpp v74, v74, v74 quad_perm:[2,3,0,1] row_mask:0xf bank_mask:0xf
	s_nop 1
	v_add_f32_dpp v74, v74, v74 row_half_mirror row_mask:0xf bank_mask:0xf
	s_nop 1
	v_add_f32_dpp v74, v74, v74 row_mirror row_mask:0xf bank_mask:0xf
	v_mov_b32_e32 v75, v74
	s_nop 1
	v_permlane16_swap_b32_e32 v75, v74
	v_add_f32_e32 v74, v74, v75
	v_fmamk_f32 v74, v74, 0x3c800000, v212
	v_cmp_gt_f32_e32 vcc, s0, v74
	v_mul_f32_e32 v75, 0x4b800000, v74
	s_nop 0
	v_cndmask_b32_e32 v74, v74, v75, vcc
	v_rsq_f32_e32 v74, v74
	s_nop 0
	v_mul_f32_e32 v75, 0x45800000, v74
	v_cndmask_b32_e32 v74, v74, v75, vcc
	v_pk_mul_f32 v[72:73], v[74:75], v[72:73] op_sel_hi:[0,1]
	v_pk_mul_f32 v[72:73], v[70:71], v[72:73]
	s_and_saveexec_b64 s[0:1], s[40:41]
	s_cbranch_execz .LBB0_325
	ds_bpermute_b32 v74, v37, v72
	ds_bpermute_b32 v75, v37, v73
	s_waitcnt lgkmcnt(0)
	v_pk_mul_f32 v[74:75], v[54:55], v[74:75]
	s_nop 0
	v_pk_fma_f32 v[72:73], v[52:53], v[72:73], v[74:75]
.LBB0_325:
	s_or_b64 exec, exec, s[0:1]
	s_mov_b32 s0, 0x3e38aa3b
	v_pk_mul_f32 v[72:73], v[72:73], s[0:1] op_sel_hi:[1,0]
	s_mov_b32 s0, 0x800000
	v_cvt_pk_bf16_f32 v81, v72, v73
	v_lshl_add_u64 v[72:73], v[68:69], 0, v[116:117]
	v_add_co_u32_e32 v74, vcc, 0x126ce000, v72
	s_nop 1
	v_addc_co_u32_e32 v75, vcc, 0, v73, vcc
	global_store_dword v[74:75], v81, off offset:512
	v_lshlrev_b32_e32 v74, 16, v80
	v_and_b32_e32 v75, 0xffff0000, v80
	v_pk_mul_f32 v[80:81], v[74:75], v[74:75]
	s_nop 0
	v_add_f32_e32 v80, v80, v81
	s_waitcnt lgkmcnt(0)
	s_nop 1
	v_add_f32_dpp v80, v80, v80 quad_perm:[1,0,3,2] row_mask:0xf bank_mask:0xf
	s_nop 1
	v_add_f32_dpp v80, v80, v80 quad_perm:[2,3,0,1] row_mask:0xf bank_mask:0xf
	s_nop 1
	v_add_f32_dpp v80, v80, v80 row_half_mirror row_mask:0xf bank_mask:0xf
	s_nop 1
	v_add_f32_dpp v80, v80, v80 row_mirror row_mask:0xf bank_mask:0xf
	v_mov_b32_e32 v81, v80
	s_nop 1
	v_permlane16_swap_b32_e32 v81, v80
	v_add_f32_e32 v80, v80, v81
	v_fmamk_f32 v80, v80, 0x3c800000, v212
	v_cmp_gt_f32_e32 vcc, s0, v80
	v_mul_f32_e32 v81, 0x4b800000, v80
	s_nop 0
	v_cndmask_b32_e32 v80, v80, v81, vcc
	v_rsq_f32_e32 v80, v80
	s_nop 0
	v_mul_f32_e32 v81, 0x45800000, v80
	v_cndmask_b32_e32 v80, v80, v81, vcc
	v_pk_mul_f32 v[74:75], v[80:81], v[74:75] op_sel_hi:[0,1]
	v_pk_mul_f32 v[70:71], v[70:71], v[74:75]
	s_and_saveexec_b64 s[0:1], s[40:41]
	s_cbranch_execz .LBB0_327
	ds_bpermute_b32 v74, v37, v70
	ds_bpermute_b32 v75, v37, v71
	s_waitcnt lgkmcnt(0)
	v_pk_mul_f32 v[74:75], v[54:55], v[74:75]
	s_nop 0
	v_pk_fma_f32 v[70:71], v[52:53], v[70:71], v[74:75]
.LBB0_327:
	s_or_b64 exec, exec, s[0:1]
	s_mov_b32 s0, 0x3e38aa3b
	v_pk_mul_f32 v[70:71], v[70:71], s[0:1] op_sel_hi:[1,0]
	s_mov_b32 s0, 0x800000
	v_cvt_pk_bf16_f32 v74, v70, v71
	v_add_co_u32_e32 v70, vcc, 0x126ce000, v72
	s_nop 1
	v_addc_co_u32_e32 v71, vcc, 0, v73, vcc
	global_store_dword v[70:71], v74, off offset:768
	v_lshlrev_b32_e32 v70, 16, v79
	v_and_b32_e32 v71, 0xffff0000, v79
	v_pk_mul_f32 v[72:73], v[70:71], v[70:71]
	s_nop 0
	v_add_f32_e32 v72, v72, v73
	s_waitcnt lgkmcnt(0)
	s_nop 1
	v_add_f32_dpp v72, v72, v72 quad_perm:[1,0,3,2] row_mask:0xf bank_mask:0xf
	s_nop 1
	v_add_f32_dpp v72, v72, v72 quad_perm:[2,3,0,1] row_mask:0xf bank_mask:0xf
	s_nop 1
	v_add_f32_dpp v72, v72, v72 row_half_mirror row_mask:0xf bank_mask:0xf
	s_nop 1
	v_add_f32_dpp v72, v72, v72 row_mirror row_mask:0xf bank_mask:0xf
	v_mov_b32_e32 v73, v72
	s_nop 1
	v_permlane16_swap_b32_e32 v73, v72
	v_add_f32_e32 v72, v72, v73
	v_fmamk_f32 v72, v72, 0x3c800000, v212
	v_cmp_gt_f32_e32 vcc, s0, v72
	v_mul_f32_e32 v73, 0x4b800000, v72
	s_nop 0
	v_cndmask_b32_e32 v72, v72, v73, vcc
	v_rsq_f32_e32 v72, v72
	s_nop 0
	v_mul_f32_e32 v73, 0x45800000, v72
	v_cndmask_b32_e32 v72, v72, v73, vcc
	v_pk_mul_f32 v[70:71], v[72:73], v[70:71] op_sel_hi:[0,1]
	v_pk_mul_f32 v[72:73], v[64:65], v[70:71]
	s_and_saveexec_b64 s[0:1], s[40:41]
	s_cbranch_execz .LBB0_329
	ds_bpermute_b32 v64, v37, v72
	ds_bpermute_b32 v65, v37, v73
	s_waitcnt lgkmcnt(0)
	v_pk_mul_f32 v[64:65], v[54:55], v[64:65]
	s_nop 0
	v_pk_fma_f32 v[72:73], v[52:53], v[72:73], v[64:65]

.LBB0_333:
	s_or_b64 exec, exec, s[0:1]
	v_lshlrev_b32_e32 v74, 16, v77
	v_and_b32_e32 v75, 0xffff0000, v77
	v_pk_mul_f32 v[80:81], v[74:75], v[74:75]
	s_mov_b32 s0, 0x800000
	v_add_f32_e32 v63, v80, v81
	s_waitcnt lgkmcnt(0)
	s_nop 1
	v_add_f32_dpp v63, v63, v63 quad_perm:[1,0,3,2] row_mask:0xf bank_mask:0xf
	s_nop 1
	v_add_f32_dpp v63, v63, v63 quad_perm:[2,3,0,1] row_mask:0xf bank_mask:0xf
	s_nop 1
	v_add_f32_dpp v63, v63, v63 row_half_mirror row_mask:0xf bank_mask:0xf
	s_nop 1
	v_add_f32_dpp v63, v63, v63 row_mirror row_mask:0xf bank_mask:0xf
	v_mov_b32_e32 v77, v63
	s_nop 1
	v_permlane16_swap_b32_e32 v77, v63
	v_add_f32_e32 v63, v63, v77
	v_fmamk_f32 v63, v63, 0x3c800000, v212
	v_mul_f32_e32 v77, 0x4b800000, v63
	v_cmp_gt_f32_e32 vcc, s0, v63
	s_nop 1
	v_cndmask_b32_e32 v63, v63, v77, vcc
	v_rsq_f32_e32 v63, v63
	s_nop 0
	v_mul_f32_e32 v77, 0x45800000, v63
	v_cndmask_b32_e32 v80, v63, v77, vcc
	v_pk_mul_f32 v[74:75], v[80:81], v[74:75] op_sel_hi:[0,1]
	v_pk_mul_f32 v[74:75], v[60:61], v[74:75]
	s_and_saveexec_b64 s[0:1], s[40:41]
	s_cbranch_execz .LBB0_335
	ds_bpermute_b32 v80, v37, v74
	ds_bpermute_b32 v81, v37, v75
	s_waitcnt lgkmcnt(0)
	v_pk_mul_f32 v[80:81], v[54:55], v[80:81]
	s_nop 0
	v_pk_fma_f32 v[74:75], v[52:53], v[74:75], v[80:81]
.LBB0_335:
	s_or_b64 exec, exec, s[0:1]
	s_mov_b32 s0, 0x3e38aa3b
	v_pk_mul_f32 v[74:75], v[74:75], s[0:1] op_sel_hi:[1,0]
	s_mov_b32 s0, 0x800000
	v_cvt_pk_bf16_f32 v63, v74, v75
	v_lshl_add_u64 v[74:75], v[68:69], 0, v[116:117]
	v_add_co_u32_e32 v80, vcc, 0x12cce000, v74
	s_nop 1
	v_addc_co_u32_e32 v81, vcc, 0, v75, vcc
	global_store_dword v[80:81], v63, off
	v_lshlrev_b32_e32 v80, 16, v76
	v_and_b32_e32 v81, 0xffff0000, v76
	v_pk_mul_f32 v[76:77], v[80:81], v[80:81]
	s_nop 0
	v_add_f32_e32 v63, v76, v77
	s_waitcnt lgkmcnt(0)
	s_nop 1
	v_add_f32_dpp v63, v63, v63 quad_perm:[1,0,3,2] row_mask:0xf bank_mask:0xf
	s_nop 1
	v_add_f32_dpp v63, v63, v63 quad_perm:[2,3,0,1] row_mask:0xf bank_mask:0xf
	s_nop 1
	v_add_f32_dpp v63, v63, v63 row_half_mirror row_mask:0xf bank_mask:0xf
	s_nop 1
	v_add_f32_dpp v63, v63, v63 row_mirror row_mask:0xf bank_mask:0xf
	v_mov_b32_e32 v76, v63
	s_nop 1
	v_permlane16_swap_b32_e32 v76, v63
	v_add_f32_e32 v63, v63, v76
	v_fmamk_f32 v63, v63, 0x3c800000, v212
	v_cmp_gt_f32_e32 vcc, s0, v63
	v_mul_f32_e32 v76, 0x4b800000, v63
	s_nop 0
	v_cndmask_b32_e32 v63, v63, v76, vcc
	v_rsq_f32_e32 v63, v63
	s_nop 0
	v_mul_f32_e32 v76, 0x45800000, v63
	v_cndmask_b32_e32 v76, v63, v76, vcc
	v_pk_mul_f32 v[76:77], v[76:77], v[80:81] op_sel_hi:[0,1]
	v_pk_mul_f32 v[76:77], v[60:61], v[76:77]
	s_and_saveexec_b64 s[0:1], s[40:41]
	s_cbranch_execz .LBB0_337
	ds_bpermute_b32 v80, v37, v76
	ds_bpermute_b32 v81, v37, v77
	s_waitcnt lgkmcnt(0)
	v_pk_mul_f32 v[80:81], v[54:55], v[80:81]
	s_nop 0
	v_pk_fma_f32 v[76:77], v[52:53], v[76:77], v[80:81]
.LBB0_337:
	s_or_b64 exec, exec, s[0:1]
	s_mov_b32 s0, 0x3e38aa3b
	v_pk_mul_f32 v[76:77], v[76:77], s[0:1] op_sel_hi:[1,0]
	v_add_co_u32_e32 v74, vcc, 0x12cce000, v74
	v_cvt_pk_bf16_f32 v63, v76, v77
	s_nop 0
	v_addc_co_u32_e32 v75, vcc, 0, v75, vcc
	global_store_dword v[74:75], v63, off offset:256
	v_lshlrev_b32_e32 v74, 16, v78
	v_and_b32_e32 v75, 0xffff0000, v78
	v_pk_mul_f32 v[76:77], v[74:75], v[74:75]
	s_mov_b32 s0, 0x800000
	v_add_f32_e32 v63, v76, v77
	s_waitcnt lgkmcnt(0)
	s_nop 1
	v_add_f32_dpp v63, v63, v63 quad_perm:[1,0,3,2] row_mask:0xf bank_mask:0xf
	s_nop 1
	v_add_f32_dpp v63, v63, v63 quad_perm:[2,3,0,1] row_mask:0xf bank_mask:0xf
	s_nop 1
	v_add_f32_dpp v63, v63, v63 row_half_mirror row_mask:0xf bank_mask:0xf
	s_nop 1
	v_add_f32_dpp v63, v63, v63 row_mirror row_mask:0xf bank_mask:0xf
	v_mov_b32_e32 v76, v63
	s_nop 1
	v_permlane16_swap_b32_e32 v76, v63
	v_add_f32_e32 v63, v63, v76
	v_fmamk_f32 v63, v63, 0x3c800000, v212
	v_cmp_gt_f32_e32 vcc, s0, v63
	v_mul_f32_e32 v76, 0x4b800000, v63
	s_nop 0
	v_cndmask_b32_e32 v63, v63, v76, vcc
	v_rsq_f32_e32 v63, v63
	s_nop 0
	v_mul_f32_e32 v76, 0x45800000, v63
	v_cndmask_b32_e32 v76, v63, v76, vcc
	v_pk_mul_f32 v[74:75], v[76:77], v[74:75] op_sel_hi:[0,1]
	v_pk_mul_f32 v[74:75], v[60:61], v[74:75]
	s_and_saveexec_b64 s[0:1], s[40:41]
	s_cbranch_execz .LBB0_339
	ds_bpermute_b32 v76, v37, v74
	ds_bpermute_b32 v77, v37, v75
	s_waitcnt lgkmcnt(0)
	v_pk_mul_f32 v[76:77], v[54:55], v[76:77]
	s_nop 0
	v_pk_fma_f32 v[74:75], v[52:53], v[74:75], v[76:77]
.LBB0_339:
	s_or_b64 exec, exec, s[0:1]
	s_mov_b32 s0, 0x3e38aa3b
	v_pk_mul_f32 v[74:75], v[74:75], s[0:1] op_sel_hi:[1,0]
	v_lshl_add_u64 v[68:69], v[68:69], 0, v[116:117]
	v_cvt_pk_bf16_f32 v63, v74, v75
	v_add_co_u32_e32 v74, vcc, 0x12cce000, v68
	s_mov_b32 s0, 0x800000
	s_nop 0
	v_addc_co_u32_e32 v75, vcc, 0, v69, vcc
	global_store_dword v[74:75], v63, off offset:512
	v_lshlrev_b32_e32 v74, 16, v49
	v_and_b32_e32 v75, 0xffff0000, v49
	v_pk_mul_f32 v[76:77], v[74:75], v[74:75]
	s_nop 0
	v_add_f32_e32 v49, v76, v77
	s_waitcnt lgkmcnt(0)
	s_nop 1
	v_add_f32_dpp v49, v49, v49 quad_perm:[1,0,3,2] row_mask:0xf bank_mask:0xf
	s_nop 1
	v_add_f32_dpp v49, v49, v49 quad_perm:[2,3,0,1] row_mask:0xf bank_mask:0xf
	s_nop 1
	v_add_f32_dpp v49, v49, v49 row_half_mirror row_mask:0xf bank_mask:0xf
	s_nop 1
	v_add_f32_dpp v49, v49, v49 row_mirror row_mask:0xf bank_mask:0xf
	v_mov_b32_e32 v63, v49
	s_nop 1
	v_permlane16_swap_b32_e32 v63, v49
	v_add_f32_e32 v49, v49, v63
	v_fmamk_f32 v49, v49, 0x3c800000, v212
	v_cmp_gt_f32_e32 vcc, s0, v49
	v_mul_f32_e32 v63, 0x4b800000, v49
	s_nop 0
	v_cndmask_b32_e32 v49, v49, v63, vcc
	v_rsq_f32_e32 v49, v49
	s_nop 0
	v_mul_f32_e32 v63, 0x45800000, v49
	v_cndmask_b32_e32 v76, v49, v63, vcc
	v_pk_mul_f32 v[74:75], v[76:77], v[74:75] op_sel_hi:[0,1]
	v_pk_mul_f32 v[60:61], v[60:61], v[74:75]
	s_and_saveexec_b64 s[0:1], s[40:41]
	s_cbranch_execz .LBB0_341
	ds_bpermute_b32 v74, v37, v60
	ds_bpermute_b32 v75, v37, v61
	s_waitcnt lgkmcnt(0)
	v_pk_mul_f32 v[74:75], v[54:55], v[74:75]
	s_nop 0
	v_pk_fma_f32 v[60:61], v[52:53], v[60:61], v[74:75]
.LBB0_341:
	s_or_b64 exec, exec, s[0:1]
	s_mov_b32 s0, 0x3e38aa3b
	v_pk_mul_f32 v[60:61], v[60:61], s[0:1] op_sel_hi:[1,0]
	s_mov_b32 s0, 0x800000
	v_cvt_pk_bf16_f32 v49, v60, v61
	v_add_co_u32_e32 v60, vcc, 0x12cce000, v68
	s_nop 1
	v_addc_co_u32_e32 v61, vcc, 0, v69, vcc
	global_store_dword v[60:61], v49, off offset:768
	v_lshlrev_b32_e32 v60, 16, v35
	v_and_b32_e32 v61, 0xffff0000, v35
	v_pk_mul_f32 v[68:69], v[60:61], v[60:61]
	s_nop 0
	v_add_f32_e32 v35, v68, v69
	s_waitcnt lgkmcnt(0)
	s_nop 1
	v_add_f32_dpp v35, v35, v35 quad_perm:[1,0,3,2] row_mask:0xf bank_mask:0xf
	s_nop 1
	v_add_f32_dpp v35, v35, v35 quad_perm:[2,3,0,1] row_mask:0xf bank_mask:0xf
	s_nop 1
	v_add_f32_dpp v35, v35, v35 row_half_mirror row_mask:0xf bank_mask:0xf
	s_nop 1
	v_add_f32_dpp v35, v35, v35 row_mirror row_mask:0xf bank_mask:0xf
	v_mov_b32_e32 v39, v35
	s_nop 1
	v_permlane16_swap_b32_e32 v39, v35
	v_add_f32_e32 v35, v35, v39
	v_fmamk_f32 v35, v35, 0x3c800000, v212
	v_cmp_gt_f32_e32 vcc, s0, v35
	v_mul_f32_e32 v39, 0x4b800000, v35
	s_nop 0
	v_cndmask_b32_e32 v35, v35, v39, vcc
	v_rsq_f32_e32 v35, v35
	s_nop 0
	v_mul_f32_e32 v39, 0x45800000, v35
	v_cndmask_b32_e32 v68, v35, v39, vcc
	v_pk_mul_f32 v[60:61], v[68:69], v[60:61] op_sel_hi:[0,1]
	v_pk_mul_f32 v[58:59], v[58:59], v[60:61]
	s_and_saveexec_b64 s[0:1], s[40:41]
	s_cbranch_execz .LBB0_343
	ds_bpermute_b32 v60, v37, v58
	ds_bpermute_b32 v61, v37, v59
	s_waitcnt lgkmcnt(0)
	v_pk_mul_f32 v[54:55], v[54:55], v[60:61]
	s_nop 0
	v_pk_fma_f32 v[58:59], v[52:53], v[58:59], v[54:55]
